# conv_win8: column-scale loads issued ahead of the data loads (both item kinds); p0_mod first strip of a column block also loaded in one batch
# baseline (speedup 1.0000x reference)
.LBB0_124:
	s_and_b32 s1, s19, 0xff
	s_ashr_i32 s0, s19, 8
	s_add_i32 s2, s1, 64
	v_readlane_b32 s40, v254, 19
	s_cmpk_lt_u32 s1, 0xc0
	s_mul_i32 s6, s0, 0x280000
	v_readlane_b32 s48, v254, 27
	s_cselect_b32 s1, s1, s2
	s_mul_hi_i32 s2, s0, 0x280000
	v_readlane_b32 s49, v254, 28
	s_add_u32 s6, s48, s6
	s_addc_u32 s2, s49, s2
	s_lshl_b32 s20, s1, 5
	s_lshl_b32 s7, s1, 7
	s_add_u32 s8, s6, s7
	s_addc_u32 s9, s2, 0
	s_lshl_b32 s6, s0, 6
	s_sub_i32 s2, s1, 64
	s_lshl_b32 s21, s1, 17
	s_ashr_i32 s7, s6, 31
	s_cmpk_gt_u32 s2, 0x7f
	s_mov_b64 s[0:1], -1
	v_readlane_b32 s41, v254, 20
	v_readlane_b32 s42, v254, 21
	v_readlane_b32 s43, v254, 22
	v_readlane_b32 s44, v254, 23
	v_readlane_b32 s45, v254, 24
	v_readlane_b32 s46, v254, 25
	v_readlane_b32 s47, v254, 26
	v_readlane_b32 s50, v254, 29
	v_readlane_b32 s51, v254, 30
	v_readlane_b32 s52, v254, 31
	v_readlane_b32 s53, v254, 32
	v_readlane_b32 s54, v254, 33
	v_readlane_b32 s55, v254, 34
	s_cbranch_scc0 .LBB0_126
	v_lshl_add_u64 v[66:67], s[8:9], 0, v[142:143]
	v_mov_b32_e32 v17, v143
	v_lshl_add_u64 v[70:71], v[66:67], 0, v[16:17]
	v_add_co_u32_e32 v46, vcc, s13, v70
	v_mov_b32_e32 v19, v143
	s_nop 0
	v_addc_co_u32_e32 v47, vcc, 0, v71, vcc
	v_add_co_u32_e32 v50, vcc, s14, v70
	v_mov_b32_e32 v21, v143
	s_nop 0
	v_addc_co_u32_e32 v51, vcc, 0, v71, vcc
	v_lshl_add_u64 v[54:55], v[66:67], 0, v[18:19]
	v_lshl_add_u64 v[58:59], v[66:67], 0, v[20:21]
	v_mov_b32_e32 v214, s20
	v_mov_b32_e32 v215, 0
	v_lshlrev_b32_e32 v214, 2, v214
	v_lshl_add_u64 v[214:215], v[2:3], 0, v[214:215]
	global_load_dword v216, v[214:215], off
	global_load_dword v217, v[214:215], off offset:64
	global_load_dwordx4 v[42:45], v[70:71], off
	s_nop 0
	global_load_dwordx4 v[46:49], v[46:47], off
	v_mov_b32_e32 v23, v143
	global_load_dwordx4 v[50:53], v[50:51], off
	s_nop 0
	global_load_dwordx4 v[54:57], v[54:55], off
	s_nop 0
	global_load_dwordx4 v[58:61], v[58:59], off
	v_lshl_add_u64 v[62:63], v[66:67], 0, v[22:23]
	global_load_dwordx4 v[62:65], v[62:63], off
	v_mov_b32_e32 v25, v143
	v_lshl_add_u64 v[66:67], v[66:67], 0, v[24:25]
	global_load_dwordx4 v[66:69], v[66:67], off
	v_add_co_u32_e32 v70, vcc, s15, v70
	s_add_u32 s0, s5, s21
	s_nop 0
	v_addc_co_u32_e32 v71, vcc, 0, v71, vcc
	global_load_dwordx4 v[70:73], v[70:71], off
	s_addc_u32 s1, s12, 0
	s_add_u32 s0, s0, s6
	s_addc_u32 s1, s1, s7
	s_lshl_b32 s2, s20, 2
	v_lshl_add_u64 v[74:75], v[2:3], 0, s[2:3]
	s_waitcnt vmcnt(7)
	ds_write2_b32 v173, v42, v43 offset1:1
	ds_write2_b32 v173, v44, v45 offset0:2 offset1:3
	s_waitcnt vmcnt(4)
	ds_write2_b32 v33, v54, v55 offset1:1
	ds_write2_b32 v34, v56, v57 offset1:1
	s_waitcnt vmcnt(3)
	ds_write2_b32 v35, v58, v59 offset1:1
	ds_write2_b32 v36, v60, v61 offset1:1
	s_waitcnt vmcnt(2)
	ds_write2_b32 v37, v62, v63 offset1:1
	ds_write2_b32 v38, v64, v65 offset1:1
	s_waitcnt vmcnt(1)
	ds_write2_b32 v39, v66, v67 offset1:1
	ds_write2_b32 v40, v68, v69 offset1:1
	ds_write2_b32 v27, v46, v47 offset1:1
	ds_write2_b32 v28, v48, v49 offset1:1
	ds_write2_b32 v29, v50, v51 offset1:1
	ds_write2_b32 v30, v52, v53 offset1:1
	s_waitcnt vmcnt(0)
	ds_write2_b32 v31, v70, v71 offset1:1
	ds_write2_b32 v32, v72, v73 offset1:1
	s_waitcnt lgkmcnt(0)
	v_mov_b32_e32 v5, v216
	v_mov_b32_e32 v9, v217
	v_lshl_add_u64 v[46:47], s[0:1], 0, v[144:145]
	ds_read2_b32 v[42:43], v149 offset1:16
	ds_read2_b32 v[44:45], v149 offset0:33 offset1:49
	ds_read2_b32 v[50:51], v149 offset0:66 offset1:82
	ds_read2_b32 v[52:53], v149 offset0:99 offset1:115
	ds_read2_b32 v[54:55], v149 offset0:132 offset1:148
	ds_read2_b32 v[56:57], v149 offset0:165 offset1:181
	ds_read2_b32 v[58:59], v149 offset0:198 offset1:214
	ds_read2_b32 v[60:61], v149 offset0:231 offset1:247
	ds_read2_b32 v[62:63], v41 offset0:8 offset1:24
	ds_read2_b32 v[64:65], v41 offset0:41 offset1:57
	ds_read2_b32 v[66:67], v41 offset0:74 offset1:90
	ds_read2_b32 v[68:69], v41 offset0:107 offset1:123
	ds_read2_b32 v[70:71], v41 offset0:140 offset1:156
	ds_read2_b32 v[72:73], v41 offset0:173 offset1:189
	ds_read2_b32 v[74:75], v41 offset0:206 offset1:222
	ds_read2_b32 v[76:77], v41 offset0:239 offset1:255
	s_waitcnt lgkmcnt(14)
	v_mov_b32_e32 v78, v42
	s_waitcnt lgkmcnt(11)
	v_mov_b32_e32 v79, v54
	v_mov_b32_e32 v54, v43
	v_mov_b32_e32 v80, v44
	s_waitcnt lgkmcnt(10)
	v_mov_b32_e32 v81, v56
	v_mov_b32_e32 v82, v50
	s_waitcnt lgkmcnt(9)
	v_mov_b32_e32 v83, v58
	v_mov_b32_e32 v84, v52
	s_waitcnt lgkmcnt(8)
	v_mov_b32_e32 v85, v60
	s_waitcnt lgkmcnt(7)
	v_mov_b32_e32 v86, v62
	s_waitcnt lgkmcnt(3)
	v_mov_b32_e32 v87, v70
	v_mov_b32_e32 v88, v64
	s_waitcnt lgkmcnt(2)
	v_mov_b32_e32 v89, v72
	v_mov_b32_e32 v90, v66
	s_waitcnt lgkmcnt(1)
	v_mov_b32_e32 v91, v74
	v_mov_b32_e32 v92, v68
	s_waitcnt lgkmcnt(0)
	v_mov_b32_e32 v93, v76
	v_mov_b32_e32 v56, v45
	v_mov_b32_e32 v58, v51
	v_mov_b32_e32 v60, v53
	v_lshl_add_u64 v[48:49], v[46:47], 0, v[6:7]
	v_mov_b32_e32 v72, v65
	v_mov_b32_e32 v76, v69
	v_mov_b32_e32 v70, v63
	v_mov_b32_e32 v74, v67
	v_lshl_add_u64 v[46:47], v[46:47], 0, v[146:147]
	s_waitcnt vmcnt(1)
	v_div_scale_f32 v11, s[0:1], v5, v5, s16
	s_waitcnt vmcnt(0)
	v_div_scale_f32 v15, s[0:1], v9, v9, s16
	v_rcp_f32_e32 v17, v11
	v_rcp_f32_e32 v19, v15
	v_div_scale_f32 v13, vcc, s16, v5, s16
	v_fma_f32 v23, -v11, v17, 1.0
	v_fma_f32 v25, -v15, v19, 1.0
	v_fmac_f32_e32 v17, v23, v17
	v_div_scale_f32 v21, s[0:1], s16, v9, s16
	v_fmac_f32_e32 v19, v25, v19
	v_mul_f32_e32 v23, v13, v17
	v_mul_f32_e32 v25, v21, v19
	v_fma_f32 v42, -v11, v23, v13
	v_fma_f32 v43, -v15, v25, v21
	v_fmac_f32_e32 v23, v42, v17
	v_fmac_f32_e32 v25, v43, v19
	v_fma_f32 v11, -v11, v23, v13
	v_fma_f32 v13, -v15, v25, v21
	v_div_fmas_f32 v11, v11, v17, v23
	s_mov_b64 vcc, s[0:1]
	v_div_fixup_f32 v11, v11, v5, s16
	v_div_fmas_f32 v13, v13, v19, v25
	v_cmp_lt_f32_e32 vcc, 0, v5
	v_div_fixup_f32 v5, v13, v9, s16
	s_nop 0
	v_cndmask_b32_e32 v42, 0, v11, vcc
	v_pk_fma_f32 v[44:45], v[78:79], v[42:43], s[4:5] op_sel_hi:[1,0,0]
	v_pk_fma_f32 v[50:51], v[80:81], v[42:43], s[4:5] op_sel_hi:[1,0,0]
	v_pk_fma_f32 v[52:53], v[82:83], v[42:43], s[4:5] op_sel_hi:[1,0,0]
	v_pk_fma_f32 v[78:79], v[84:85], v[42:43], s[4:5] op_sel_hi:[1,0,0]
	v_pk_fma_f32 v[80:81], v[86:87], v[42:43], s[4:5] op_sel_hi:[1,0,0]
	v_pk_fma_f32 v[82:83], v[88:89], v[42:43], s[4:5] op_sel_hi:[1,0,0]
	v_pk_fma_f32 v[84:85], v[90:91], v[42:43], s[4:5] op_sel_hi:[1,0,0]
	v_pk_fma_f32 v[42:43], v[92:93], v[42:43], s[4:5] op_sel_hi:[1,0,0]
	v_cmp_lt_f32_e32 vcc, 0, v9
	v_lshlrev_b32_e32 v9, 8, v50
	v_lshlrev_b32_e32 v15, 24, v79
	v_cndmask_b32_e32 v62, 0, v5, vcc
	v_lshlrev_b32_e32 v5, 8, v51
	v_lshlrev_b32_e32 v17, 24, v78
	v_lshlrev_b32_e32 v19, 8, v83
	v_lshlrev_b32_e32 v21, 8, v82
	v_lshlrev_b32_e32 v64, 24, v43
	v_lshlrev_b32_e32 v66, 24, v42
	v_lshlrev_b32_e32 v11, 16, v53
	v_lshlrev_b32_e32 v13, 16, v52
	v_lshlrev_b32_e32 v23, 16, v85
	v_lshlrev_b32_e32 v25, 16, v84
	v_pk_fma_f32 v[42:43], v[54:55], v[62:63], s[4:5] op_sel_hi:[1,0,0]
	v_pk_fma_f32 v[50:51], v[56:57], v[62:63], s[4:5] op_sel_hi:[1,0,0]
	v_pk_fma_f32 v[52:53], v[58:59], v[62:63], s[4:5] op_sel_hi:[1,0,0]
	v_pk_fma_f32 v[54:55], v[60:61], v[62:63], s[4:5] op_sel_hi:[1,0,0]
	v_and_b32_e32 v5, 0xff00, v5
	v_and_b32_e32 v9, 0xff00, v9
	v_or_b32_sdwa v15, v15, v45 dst_sel:DWORD dst_unused:UNUSED_PAD src0_sel:DWORD src1_sel:BYTE_0
	v_or_b32_sdwa v17, v17, v44 dst_sel:DWORD dst_unused:UNUSED_PAD src0_sel:DWORD src1_sel:BYTE_0
	v_and_b32_e32 v19, 0xff00, v19
	v_and_b32_e32 v21, 0xff00, v21
	v_or_b32_sdwa v44, v64, v81 dst_sel:DWORD dst_unused:UNUSED_PAD src0_sel:DWORD src1_sel:BYTE_0
	v_or_b32_sdwa v45, v66, v80 dst_sel:DWORD dst_unused:UNUSED_PAD src0_sel:DWORD src1_sel:BYTE_0
	v_and_b32_e32 v11, 0xff0000, v11
	v_and_b32_e32 v13, 0xff0000, v13
	v_and_b32_e32 v23, 0xff0000, v23
	v_and_b32_e32 v25, 0xff0000, v25
	v_lshlrev_b32_e32 v51, 8, v51
	v_lshlrev_b32_e32 v50, 8, v50
	v_lshlrev_b32_e32 v53, 16, v53
	v_lshlrev_b32_e32 v52, 16, v52
	v_lshlrev_b32_e32 v55, 24, v55
	v_lshlrev_b32_e32 v54, 24, v54
	v_or_b32_e32 v5, v15, v5
	v_or_b32_e32 v9, v17, v9
	v_or_b32_e32 v15, v44, v19
	v_or_b32_e32 v17, v45, v21
	v_and_b32_e32 v19, 0xff00, v51
	v_and_b32_e32 v21, 0xff00, v50
	v_and_b32_e32 v50, 0xff0000, v53
	v_and_b32_e32 v51, 0xff0000, v52
	v_or_b32_sdwa v52, v55, v43 dst_sel:DWORD dst_unused:UNUSED_PAD src0_sel:DWORD src1_sel:BYTE_0
	v_or_b32_sdwa v53, v54, v42 dst_sel:DWORD dst_unused:UNUSED_PAD src0_sel:DWORD src1_sel:BYTE_0
	v_or_b32_e32 v43, v5, v11
	v_or_b32_e32 v42, v9, v13
	v_or_b32_e32 v45, v15, v23
	v_or_b32_e32 v44, v17, v25
	v_or_b32_e32 v5, v52, v19
	v_or_b32_e32 v9, v53, v21
	global_store_dwordx4 v[48:49], v[42:45], off
	v_pk_fma_f32 v[48:49], v[72:73], v[62:63], s[4:5] op_sel_hi:[1,0,0]
	v_pk_fma_f32 v[52:53], v[76:77], v[62:63], s[4:5] op_sel_hi:[1,0,0]
	v_or_b32_e32 v43, v5, v50
	v_or_b32_e32 v42, v9, v51
	v_pk_fma_f32 v[44:45], v[70:71], v[62:63], s[4:5] op_sel_hi:[1,0,0]
	v_pk_fma_f32 v[50:51], v[74:75], v[62:63], s[4:5] op_sel_hi:[1,0,0]
	v_lshlrev_b32_e32 v5, 8, v49
	v_lshlrev_b32_e32 v9, 8, v48
	v_lshlrev_b32_e32 v15, 24, v53
	v_lshlrev_b32_e32 v17, 24, v52
	v_and_b32_e32 v5, 0xff00, v5
	v_and_b32_e32 v9, 0xff00, v9
	v_lshlrev_b32_e32 v11, 16, v51
	v_lshlrev_b32_e32 v13, 16, v50
	v_or_b32_sdwa v15, v15, v45 dst_sel:DWORD dst_unused:UNUSED_PAD src0_sel:DWORD src1_sel:BYTE_0
	v_or_b32_sdwa v17, v17, v44 dst_sel:DWORD dst_unused:UNUSED_PAD src0_sel:DWORD src1_sel:BYTE_0
	v_and_b32_e32 v11, 0xff0000, v11
	v_and_b32_e32 v13, 0xff0000, v13
	v_or_b32_e32 v5, v15, v5
	v_or_b32_e32 v9, v17, v9
	v_or_b32_e32 v45, v5, v11
	v_or_b32_e32 v44, v9, v13
	global_store_dwordx4 v[46:47], v[42:45], off
	s_waitcnt lgkmcnt(0)
	s_cbranch_execnz .LBB0_123
	s_branch .LBB0_127

.LBB0_127:
	v_lshl_add_u64 v[62:63], s[8:9], 0, v[142:143]
	v_mov_b32_e32 v17, v143
	v_lshl_add_u64 v[70:71], v[62:63], 0, v[16:17]
	v_add_co_u32_e32 v46, vcc, s13, v70
	v_mov_b32_e32 v19, v143
	s_nop 0
	v_addc_co_u32_e32 v47, vcc, 0, v71, vcc
	v_add_co_u32_e32 v66, vcc, s14, v70
	v_mov_b32_e32 v21, v143
	v_mov_b32_e32 v23, v143
	v_mov_b32_e32 v25, v143
	v_addc_co_u32_e32 v67, vcc, 0, v71, vcc
	v_lshl_add_u64 v[50:51], v[62:63], 0, v[18:19]
	v_lshl_add_u64 v[54:55], v[62:63], 0, v[20:21]
	v_lshl_add_u64 v[58:59], v[62:63], 0, v[22:23]
	v_lshl_add_u64 v[62:63], v[62:63], 0, v[24:25]
	v_mov_b32_e32 v214, s20
	v_mov_b32_e32 v215, 0
	v_lshlrev_b32_e32 v214, 2, v214
	v_lshl_add_u64 v[214:215], v[2:3], 0, v[214:215]
	global_load_dword v216, v[214:215], off
	global_load_dword v217, v[214:215], off offset:64
	global_load_dwordx4 v[42:45], v[70:71], off
	s_nop 0
	global_load_dwordx4 v[46:49], v[46:47], off
	s_nop 0
	global_load_dwordx4 v[50:53], v[50:51], off
	s_nop 0
	global_load_dwordx4 v[54:57], v[54:55], off
	v_add_co_u32_e32 v70, vcc, s15, v70
	global_load_dwordx4 v[58:61], v[58:59], off
	s_nop 0
	global_load_dwordx4 v[62:65], v[62:63], off
	s_nop 0
	global_load_dwordx4 v[66:69], v[66:67], off
	v_addc_co_u32_e32 v71, vcc, 0, v71, vcc
	global_load_dwordx4 v[70:73], v[70:71], off
	s_lshl_b32 s0, s21, 1
	s_add_u32 s2, s10, s0
	s_addc_u32 s8, s11, 0
	s_lshl_b64 s[0:1], s[6:7], 1
	s_add_u32 s0, s2, s0
	v_mov_b32_e32 v5, v143
	s_addc_u32 s1, s8, s1
	v_mov_b32_e32 v9, v143
	v_lshl_add_u64 v[74:75], s[0:1], 0, v[4:5]
	v_lshl_add_u64 v[76:77], v[74:75], 0, v[8:9]
	s_add_u32 s2, s5, s21
	s_addc_u32 s1, s12, 0
	s_add_u32 s0, s2, s6
	s_addc_u32 s1, s1, s7
	s_lshl_b32 s2, s20, 2
	s_waitcnt vmcnt(7)
	ds_write2_b32 v173, v42, v43 offset1:1
	ds_write2_b32 v173, v44, v45 offset0:2 offset1:3
	s_waitcnt vmcnt(5)
	ds_write2_b32 v33, v50, v51 offset1:1
	ds_write2_b32 v34, v52, v53 offset1:1
	s_waitcnt vmcnt(4)
	ds_write2_b32 v35, v54, v55 offset1:1
	ds_write2_b32 v36, v56, v57 offset1:1
	s_waitcnt vmcnt(3)
	ds_write2_b32 v37, v58, v59 offset1:1
	ds_write2_b32 v38, v60, v61 offset1:1
	s_waitcnt vmcnt(2)
	ds_write2_b32 v39, v62, v63 offset1:1
	ds_write2_b32 v40, v64, v65 offset1:1
	ds_write2_b32 v27, v46, v47 offset1:1
	ds_write2_b32 v28, v48, v49 offset1:1
	s_waitcnt vmcnt(1)
	ds_write2_b32 v29, v66, v67 offset1:1
	ds_write2_b32 v30, v68, v69 offset1:1
	s_waitcnt vmcnt(0)
	ds_write2_b32 v31, v70, v71 offset1:1
	ds_write2_b32 v32, v72, v73 offset1:1
	s_waitcnt lgkmcnt(0)
	ds_read2_b32 v[46:47], v26 offset0:33 offset1:41
	ds_read2_b32 v[48:49], v26 offset1:8
	ds_read2_b32 v[50:51], v26 offset0:66 offset1:74
	ds_read2_b32 v[52:53], v26 offset0:99 offset1:107
	ds_read2_b32 v[54:55], v26 offset0:132 offset1:140
	ds_read2_b32 v[56:57], v26 offset0:165 offset1:173
	ds_read2_b32 v[58:59], v26 offset0:198 offset1:206
	ds_read2_b32 v[60:61], v26 offset0:231 offset1:239
	s_waitcnt lgkmcnt(6)
	v_bfe_u32 v5, v48, 16, 1
	v_bfe_u32 v9, v46, 16, 1
	v_add3_u32 v5, v48, v5, s17
	s_waitcnt lgkmcnt(5)
	v_bfe_u32 v11, v50, 16, 1
	s_waitcnt lgkmcnt(3)
	v_bfe_u32 v15, v54, 16, 1
	s_waitcnt lgkmcnt(1)
	v_bfe_u32 v19, v58, 16, 1
	v_add3_u32 v9, v46, v9, s17
	v_lshrrev_b32_e32 v5, 16, v5
	v_bfe_u32 v13, v52, 16, 1
	v_bfe_u32 v17, v56, 16, 1
	s_waitcnt lgkmcnt(0)
	v_bfe_u32 v21, v60, 16, 1
	v_add3_u32 v11, v50, v11, s17
	v_add3_u32 v15, v54, v15, s17
	v_add3_u32 v19, v58, v19, s17
	v_and_or_b32 v42, v9, s18, v5
	v_bfe_u32 v5, v49, 16, 1
	v_add3_u32 v13, v52, v13, s17
	v_add3_u32 v17, v56, v17, s17
	v_add3_u32 v21, v60, v21, s17
	v_lshrrev_b32_e32 v11, 16, v11
	v_lshrrev_b32_e32 v15, 16, v15
	v_lshrrev_b32_e32 v19, 16, v19
	v_add3_u32 v5, v49, v5, s17
	v_bfe_u32 v9, v47, 16, 1
	v_and_or_b32 v43, v13, s18, v11
	v_and_or_b32 v44, v17, s18, v15
	v_and_or_b32 v45, v21, s18, v19
	v_lshrrev_b32_e32 v5, 16, v5
	v_add3_u32 v9, v47, v9, s17
	global_store_dwordx4 v[76:77], v[42:45], off
	v_mov_b32_e32 v11, v143
	ds_read2_b32 v[46:47], v26 offset0:16 offset1:24
	v_and_or_b32 v42, v9, s18, v5
	v_bfe_u32 v5, v51, 16, 1
	v_add3_u32 v5, v51, v5, s17
	v_bfe_u32 v9, v53, 16, 1
	v_lshrrev_b32_e32 v5, 16, v5
	v_add3_u32 v9, v53, v9, s17
	v_and_or_b32 v43, v9, s18, v5
	v_bfe_u32 v5, v55, 16, 1
	v_add3_u32 v5, v55, v5, s17
	v_bfe_u32 v9, v57, 16, 1
	v_lshrrev_b32_e32 v5, 16, v5
	v_add3_u32 v9, v57, v9, s17
	v_and_or_b32 v44, v9, s18, v5
	v_bfe_u32 v5, v59, 16, 1
	v_add3_u32 v5, v59, v5, s17
	v_bfe_u32 v9, v61, 16, 1
	v_lshrrev_b32_e32 v5, 16, v5
	v_add3_u32 v9, v61, v9, s17
	v_and_or_b32 v45, v9, s18, v5
	v_lshl_add_u64 v[48:49], v[74:75], 0, v[10:11]
	global_store_dwordx4 v[48:49], v[42:45], off
	ds_read2_b32 v[48:49], v26 offset0:49 offset1:57
	ds_read2_b32 v[50:51], v26 offset0:82 offset1:90
	ds_read2_b32 v[52:53], v26 offset0:115 offset1:123
	s_waitcnt lgkmcnt(3)
	v_bfe_u32 v5, v46, 16, 1
	v_add3_u32 v5, v46, v5, s17
	s_waitcnt lgkmcnt(2)
	v_bfe_u32 v9, v48, 16, 1
	ds_read2_b32 v[54:55], v26 offset0:148 offset1:156
	v_lshrrev_b32_e32 v5, 16, v5
	v_add3_u32 v9, v48, v9, s17
	ds_read2_b32 v[56:57], v26 offset0:181 offset1:189
	v_and_or_b32 v42, v9, s18, v5
	s_waitcnt lgkmcnt(3)
	v_bfe_u32 v5, v50, 16, 1
	v_add3_u32 v5, v50, v5, s17
	s_waitcnt lgkmcnt(2)
	v_bfe_u32 v9, v52, 16, 1
	ds_read2_b32 v[58:59], v26 offset0:214 offset1:222
	v_lshrrev_b32_e32 v5, 16, v5
	v_add3_u32 v9, v52, v9, s17
	ds_read2_b32 v[60:61], v26 offset0:247 offset1:255
	v_and_or_b32 v43, v9, s18, v5
	s_waitcnt lgkmcnt(3)
	v_bfe_u32 v5, v54, 16, 1
	v_add3_u32 v5, v54, v5, s17
	s_waitcnt lgkmcnt(2)
	v_bfe_u32 v9, v56, 16, 1
	v_lshrrev_b32_e32 v5, 16, v5
	v_add3_u32 v9, v56, v9, s17
	v_and_or_b32 v44, v9, s18, v5
	s_waitcnt lgkmcnt(1)
	v_bfe_u32 v5, v58, 16, 1
	v_add3_u32 v5, v58, v5, s17
	s_waitcnt lgkmcnt(0)
	v_bfe_u32 v9, v60, 16, 1
	v_lshrrev_b32_e32 v5, 16, v5
	v_add3_u32 v9, v60, v9, s17
	v_and_or_b32 v45, v9, s18, v5
	v_bfe_u32 v5, v47, 16, 1
	v_mov_b32_e32 v13, v143
	v_add3_u32 v5, v47, v5, s17
	v_bfe_u32 v9, v49, 16, 1
	v_lshl_add_u64 v[62:63], v[74:75], 0, v[12:13]
	v_lshrrev_b32_e32 v5, 16, v5
	v_add3_u32 v9, v49, v9, s17
	global_store_dwordx4 v[62:63], v[42:45], off
	v_mov_b32_e32 v15, v143
	v_lshl_add_u64 v[46:47], v[74:75], 0, v[14:15]
	v_and_or_b32 v42, v9, s18, v5
	v_bfe_u32 v5, v51, 16, 1
	v_add3_u32 v5, v51, v5, s17
	v_bfe_u32 v9, v53, 16, 1
	v_lshrrev_b32_e32 v5, 16, v5
	v_add3_u32 v9, v53, v9, s17
	v_and_or_b32 v43, v9, s18, v5
	v_bfe_u32 v5, v55, 16, 1
	v_add3_u32 v5, v55, v5, s17
	v_bfe_u32 v9, v57, 16, 1
	v_lshrrev_b32_e32 v5, 16, v5
	v_add3_u32 v9, v57, v9, s17
	v_and_or_b32 v44, v9, s18, v5
	v_bfe_u32 v5, v59, 16, 1
	v_add3_u32 v5, v59, v5, s17
	v_bfe_u32 v9, v61, 16, 1
	v_lshrrev_b32_e32 v5, 16, v5
	v_add3_u32 v9, v61, v9, s17
	v_and_or_b32 v45, v9, s18, v5
	global_store_dwordx4 v[46:47], v[42:45], off
	s_nop 1
	v_lshl_add_u64 v[42:43], v[2:3], 0, s[2:3]
	v_mov_b32_e32 v5, v216
	v_mov_b32_e32 v9, v217
	ds_read2_b32 v[46:47], v149 offset1:16
	ds_read2_b32 v[48:49], v149 offset0:33 offset1:49
	ds_read2_b32 v[50:51], v149 offset0:66 offset1:82
	ds_read2_b32 v[52:53], v149 offset0:99 offset1:115
	ds_read2_b32 v[54:55], v149 offset0:132 offset1:148
	ds_read2_b32 v[56:57], v149 offset0:165 offset1:181
	ds_read2_b32 v[58:59], v149 offset0:198 offset1:214
	ds_read2_b32 v[60:61], v149 offset0:231 offset1:247
	s_waitcnt lgkmcnt(6)
	v_mov_b32_e32 v62, v48
	s_waitcnt lgkmcnt(5)
	v_mov_b32_e32 v64, v50
	s_waitcnt lgkmcnt(2)
	v_mov_b32_e32 v63, v56
	s_waitcnt lgkmcnt(1)
	v_mov_b32_e32 v65, v58
	v_mov_b32_e32 v66, v52
	s_waitcnt lgkmcnt(0)
	v_mov_b32_e32 v67, v60
	v_mov_b32_e32 v42, v46
	v_mov_b32_e32 v43, v54
	v_mov_b32_e32 v56, v49
	v_mov_b32_e32 v60, v53
	v_mov_b32_e32 v54, v47
	v_mov_b32_e32 v58, v51
	s_nop 0
	v_div_scale_f32 v11, s[6:7], v5, v5, s16
	v_rcp_f32_e32 v13, v11
	s_nop 0
	v_fma_f32 v15, -v11, v13, 1.0
	v_fmac_f32_e32 v13, v15, v13
	v_div_scale_f32 v15, vcc, s16, v5, s16
	v_mul_f32_e32 v17, v15, v13
	v_fma_f32 v19, -v11, v17, v15
	v_fmac_f32_e32 v17, v19, v13
	v_fma_f32 v11, -v11, v17, v15
	v_div_fmas_f32 v11, v11, v13, v17
	v_div_fixup_f32 v11, v11, v5, s16
	v_cmp_lt_f32_e32 vcc, 0, v5
	s_nop 1
	v_cndmask_b32_e32 v44, 0, v11, vcc
	v_pk_fma_f32 v[62:63], v[62:63], v[44:45], s[4:5] op_sel_hi:[1,0,0]
	v_pk_fma_f32 v[64:65], v[64:65], v[44:45], s[4:5] op_sel_hi:[1,0,0]
	v_pk_fma_f32 v[66:67], v[66:67], v[44:45], s[4:5] op_sel_hi:[1,0,0]
	v_lshlrev_b32_e32 v5, 8, v63
	v_lshlrev_b32_e32 v11, 8, v62
	v_lshlrev_b32_e32 v13, 16, v65
	v_lshlrev_b32_e32 v15, 16, v64
	v_lshlrev_b32_e32 v17, 24, v67
	v_lshlrev_b32_e32 v19, 24, v66
	ds_read2_b32 v[62:63], v41 offset0:8 offset1:24
	ds_read2_b32 v[64:65], v41 offset0:41 offset1:57
	ds_read2_b32 v[66:67], v41 offset0:74 offset1:90
	ds_read2_b32 v[68:69], v41 offset0:140 offset1:156
	ds_read2_b32 v[70:71], v41 offset0:107 offset1:123
	ds_read2_b32 v[72:73], v41 offset0:173 offset1:189
	ds_read2_b32 v[74:75], v41 offset0:206 offset1:222
	ds_read2_b32 v[80:81], v41 offset0:239 offset1:255
	v_pk_fma_f32 v[42:43], v[42:43], v[44:45], s[4:5] op_sel_hi:[1,0,0]
	v_and_b32_e32 v5, 0xff00, v5
	v_or_b32_sdwa v17, v17, v43 dst_sel:DWORD dst_unused:UNUSED_PAD src0_sel:DWORD src1_sel:BYTE_0
	s_waitcnt lgkmcnt(7)
	v_mov_b32_e32 v76, v62
	s_waitcnt lgkmcnt(4)
	v_mov_b32_e32 v77, v68
	v_mov_b32_e32 v78, v64
	s_waitcnt lgkmcnt(2)
	v_mov_b32_e32 v79, v72
	v_mov_b32_e32 v82, v66
	s_waitcnt lgkmcnt(1)
	v_mov_b32_e32 v83, v74
	v_mov_b32_e32 v84, v70
	s_waitcnt lgkmcnt(0)
	v_mov_b32_e32 v85, v80
	v_and_b32_e32 v11, 0xff00, v11
	v_and_b32_e32 v13, 0xff0000, v13
	v_or_b32_sdwa v19, v19, v42 dst_sel:DWORD dst_unused:UNUSED_PAD src0_sel:DWORD src1_sel:BYTE_0
	v_or_b32_e32 v5, v17, v5
	v_pk_fma_f32 v[76:77], v[76:77], v[44:45], s[4:5] op_sel_hi:[1,0,0]
	v_pk_fma_f32 v[78:79], v[78:79], v[44:45], s[4:5] op_sel_hi:[1,0,0]
	v_pk_fma_f32 v[82:83], v[82:83], v[44:45], s[4:5] op_sel_hi:[1,0,0]
	v_pk_fma_f32 v[44:45], v[84:85], v[44:45], s[4:5] op_sel_hi:[1,0,0]
	v_and_b32_e32 v15, 0xff0000, v15
	v_or_b32_e32 v11, v19, v11
	v_or_b32_e32 v43, v5, v13
	v_lshlrev_b32_e32 v5, 24, v45
	v_lshlrev_b32_e32 v13, 8, v79
	v_or_b32_e32 v42, v11, v15
	v_or_b32_sdwa v5, v5, v77 dst_sel:DWORD dst_unused:UNUSED_PAD src0_sel:DWORD src1_sel:BYTE_0
	v_lshlrev_b32_e32 v15, 8, v78
	v_and_b32_e32 v13, 0xff00, v13
	v_lshlrev_b32_e32 v17, 16, v83
	v_lshlrev_b32_e32 v11, 24, v44
	v_or_b32_e32 v5, v5, v13
	v_and_b32_e32 v13, 0xff00, v15
	v_and_b32_e32 v15, 0xff0000, v17
	v_or_b32_sdwa v11, v11, v76 dst_sel:DWORD dst_unused:UNUSED_PAD src0_sel:DWORD src1_sel:BYTE_0
	v_lshl_add_u64 v[76:77], s[0:1], 0, v[144:145]
	v_or_b32_e32 v45, v5, v15
	s_nop 0
	v_div_scale_f32 v5, s[0:1], v9, v9, s16
	v_or_b32_e32 v11, v11, v13
	v_rcp_f32_e32 v13, v5
	v_lshlrev_b32_e32 v19, 16, v82
	v_and_b32_e32 v17, 0xff0000, v19
	v_or_b32_e32 v44, v11, v17
	v_fma_f32 v11, -v5, v13, 1.0
	v_fmac_f32_e32 v13, v11, v13
	v_div_scale_f32 v11, vcc, s16, v9, s16
	v_mul_f32_e32 v15, v11, v13
	v_fma_f32 v17, -v5, v15, v11
	v_fmac_f32_e32 v15, v17, v13
	v_fma_f32 v5, -v5, v15, v11
	v_div_fmas_f32 v5, v5, v13, v15
	v_lshl_add_u64 v[78:79], v[76:77], 0, v[6:7]
	v_div_fixup_f32 v5, v5, v9, s16
	v_cmp_lt_f32_e32 vcc, 0, v9
	global_store_dwordx4 v[78:79], v[42:45], off
	v_mov_b32_e32 v68, v63
	v_mov_b32_e32 v72, v65
	v_cndmask_b32_e32 v44, 0, v5, vcc
	v_pk_fma_f32 v[46:47], v[56:57], v[44:45], s[4:5] op_sel_hi:[1,0,0]
	v_pk_fma_f32 v[50:51], v[60:61], v[44:45], s[4:5] op_sel_hi:[1,0,0]
	v_pk_fma_f32 v[42:43], v[54:55], v[44:45], s[4:5] op_sel_hi:[1,0,0]
	v_pk_fma_f32 v[48:49], v[58:59], v[44:45], s[4:5] op_sel_hi:[1,0,0]
	v_lshlrev_b32_e32 v5, 8, v47
	v_lshlrev_b32_e32 v9, 8, v46
	v_lshlrev_b32_e32 v15, 24, v51
	v_lshlrev_b32_e32 v17, 24, v50
	v_and_b32_e32 v5, 0xff00, v5
	v_and_b32_e32 v9, 0xff00, v9
	v_lshlrev_b32_e32 v11, 16, v49
	v_lshlrev_b32_e32 v13, 16, v48
	v_or_b32_sdwa v15, v15, v43 dst_sel:DWORD dst_unused:UNUSED_PAD src0_sel:DWORD src1_sel:BYTE_0
	v_or_b32_sdwa v17, v17, v42 dst_sel:DWORD dst_unused:UNUSED_PAD src0_sel:DWORD src1_sel:BYTE_0
	v_mov_b32_e32 v74, v67
	v_mov_b32_e32 v80, v71
	v_and_b32_e32 v11, 0xff0000, v11
	v_and_b32_e32 v13, 0xff0000, v13
	v_or_b32_e32 v5, v15, v5
	v_or_b32_e32 v9, v17, v9
	v_pk_fma_f32 v[46:47], v[68:69], v[44:45], s[4:5] op_sel_hi:[1,0,0]
	v_pk_fma_f32 v[48:49], v[72:73], v[44:45], s[4:5] op_sel_hi:[1,0,0]
	v_pk_fma_f32 v[50:51], v[74:75], v[44:45], s[4:5] op_sel_hi:[1,0,0]
	v_pk_fma_f32 v[44:45], v[80:81], v[44:45], s[4:5] op_sel_hi:[1,0,0]
	v_or_b32_e32 v43, v5, v11
	v_or_b32_e32 v42, v9, v13
	v_lshlrev_b32_e32 v5, 8, v49
	v_lshlrev_b32_e32 v9, 8, v48
	v_lshlrev_b32_e32 v15, 24, v45
	v_lshlrev_b32_e32 v17, 24, v44
	v_and_b32_e32 v5, 0xff00, v5
	v_and_b32_e32 v9, 0xff00, v9
	v_lshlrev_b32_e32 v11, 16, v51
	v_lshlrev_b32_e32 v13, 16, v50
	v_or_b32_sdwa v15, v15, v47 dst_sel:DWORD dst_unused:UNUSED_PAD src0_sel:DWORD src1_sel:BYTE_0
	v_or_b32_sdwa v17, v17, v46 dst_sel:DWORD dst_unused:UNUSED_PAD src0_sel:DWORD src1_sel:BYTE_0
	v_and_b32_e32 v11, 0xff0000, v11
	v_and_b32_e32 v13, 0xff0000, v13
	v_or_b32_e32 v5, v15, v5
	v_or_b32_e32 v9, v17, v9
	v_or_b32_e32 v45, v5, v11
	v_or_b32_e32 v44, v9, v13
	v_lshl_add_u64 v[46:47], v[76:77], 0, v[146:147]
	global_store_dwordx4 v[46:47], v[42:45], off
	s_waitcnt lgkmcnt(0)
	s_branch .LBB0_123

.LBB0_131:
	s_mov_b64 s[2:3], 0
	v_mov_b32_e32 v2, v178
	v_mov_b32_e32 v4, v177
	v_mov_b32_e32 v5, v1
	s_barrier
	v_cmp_gt_u32_e64 s[0:1], 32, v1
	v_mov_b32_e32 v38, s9
	v_mov_b32_e32 v39, s8
	v_mov_b32_e32 v40, s71
	v_mov_b32_e32 v41, s69
	v_cndmask_b32_e64 v44, v38, v39, s[0:1]
	v_mov_b32_e32 v42, s70
	v_mov_b32_e32 v43, s68
	v_cndmask_b32_e64 v39, v40, v41, s[0:1]
	v_add_u32_e32 v40, v44, v2
	v_cndmask_b32_e64 v38, v42, v43, s[0:1]
	v_ashrrev_i32_e32 v41, 31, v40
	v_lshl_add_u64 v[38:39], v[40:41], 2, v[38:39]
	global_load_dword v45, v[38:39], off
	v_add_u32_e32 v40, s9, v2
	v_add_u32_e32 v40, 0x4000, v40
	v_ashrrev_i32_e32 v41, 31, v40
	v_lshl_add_u64 v[38:39], v[40:41], 2, s[70:71]
	global_load_dword v46, v[38:39], off
	v_add_u32_e32 v40, 0x4000, v40
	v_ashrrev_i32_e32 v41, 31, v40
	v_lshl_add_u64 v[38:39], v[40:41], 2, s[70:71]
	global_load_dword v47, v[38:39], off
	v_add_u32_e32 v40, 0x4000, v40
	v_ashrrev_i32_e32 v41, 31, v40
	v_lshl_add_u64 v[38:39], v[40:41], 2, s[70:71]
	global_load_dword v48, v[38:39], off
	v_add_u32_e32 v40, 0x4000, v40
	v_ashrrev_i32_e32 v41, 31, v40
	v_lshl_add_u64 v[38:39], v[40:41], 2, s[70:71]
	s_and_saveexec_b64 s[2:3], s[0:1]
	global_load_dword v49, v[38:39], off
	s_mov_b64 exec, s[2:3]
	s_waitcnt vmcnt(0)
	v_mul_f32_e32 v50, 0xbfb8aa3b, v45
	v_mul_f32_e32 v51, 0xbfb8aa3b, v46
	v_mul_f32_e32 v52, 0xbfb8aa3b, v47
	v_mul_f32_e32 v53, 0xbfb8aa3b, v48
	v_mul_f32_e32 v54, 0xbfb8aa3b, v49
	v_exp_f32_e32 v50, v50
	v_exp_f32_e32 v51, v51
	v_exp_f32_e32 v52, v52
	v_exp_f32_e32 v53, v53
	v_exp_f32_e32 v54, v54
	v_add_f32_e32 v50, 1.0, v50
	v_add_f32_e32 v51, 1.0, v51
	v_add_f32_e32 v52, 1.0, v52
	v_add_f32_e32 v53, 1.0, v53
	v_add_f32_e32 v54, 1.0, v54
	v_rcp_f32_e32 v50, v50
	v_rcp_f32_e32 v51, v51
	v_rcp_f32_e32 v52, v52
	v_rcp_f32_e32 v53, v53
	v_rcp_f32_e32 v54, v54
	v_mul_f32_e32 v45, v45, v50
	v_mul_f32_e32 v46, v46, v51
	v_mul_f32_e32 v47, v47, v52
	v_mul_f32_e32 v48, v48, v53
	v_mul_f32_e32 v49, v49, v54
	ds_write_b32 v4, v45
	ds_write_b32 v4, v46 offset:16
	ds_write_b32 v4, v47 offset:32
	ds_write_b32 v4, v48 offset:48
	s_and_saveexec_b64 s[2:3], s[0:1]
	ds_write_b32 v4, v49 offset:64
	s_mov_b64 exec, s[2:3]
	s_or_b64 exec, exec, s[2:3]
	s_mul_i32 s2, s16, 0x60
	s_ashr_i32 s3, s2, 31
	v_lshl_add_u64 v[168:169], s[2:3], 2, v[150:151]
	s_and_saveexec_b64 s[0:1], vcc
	s_cbranch_execz .LBB0_135
	v_lshl_add_u64 v[4:5], v[168:169], 0, v[152:153]
	v_lshl_add_u64 v[6:7], v[168:169], 0, v[154:155]
	global_load_dwordx4 v[34:37], v[4:5], off
	global_load_dwordx4 v[30:33], v[6:7], off
	v_lshl_add_u64 v[4:5], v[168:169], 0, v[156:157]
	v_lshl_add_u64 v[6:7], v[168:169], 0, v[158:159]
	global_load_dwordx4 v[26:29], v[4:5], off
	global_load_dwordx4 v[22:25], v[6:7], off
	v_lshl_add_u64 v[4:5], v[168:169], 0, v[160:161]
	v_lshl_add_u64 v[6:7], v[168:169], 0, v[162:163]
	global_load_dwordx4 v[18:21], v[4:5], off
	global_load_dwordx4 v[14:17], v[6:7], off
	v_lshl_add_u64 v[4:5], v[168:169], 0, v[164:165]
	v_lshl_add_u64 v[6:7], v[168:169], 0, v[166:167]
	global_load_dwordx4 v[10:13], v[4:5], off
	s_nop 0
	global_load_dwordx4 v[6:9], v[6:7], off
